# kernel entry: the three other kernarg cache lines touched right behind the first s_load so later scalar loads hit the scalar cache
# baseline (speedup 1.0000x reference)
; DI unsigned xb_add(unsigned* p, unsigned v) { return __hip_atomic_fetch_add(p, v, __ATOMIC_RELAXED, __HIP_MEMORY_SCOPE_AGENT); }
; DI unsigned xb_xcc_id() { return (unsigned)__builtin_amdgcn_s_getreg((3 << 11) | 20) & 0xFu; }
; __global__ void __launch_bounds__(512, 2) fwd_megakernel(Params p) {
;     extern __shared__ __attribute__((aligned(16))) unsigned char lds[];
;     cg::grid_group grid = cg::this_grid();
;     unsigned* bar = (unsigned*)(p.ws + OFF_BAR);
;     __shared__ __attribute__((aligned(16))) unsigned xb_st[4];
;     volatile __attribute__((address_space(3))) unsigned* st = (volatile __attribute__((address_space(3))) unsigned*)xb_st;
;     if (threadIdx.x < 4) xb_st[threadIdx.x] = 0u;
;     __syncthreads();
;     if (threadIdx.x == 0) (void)xb_add(&bar[XB_XCNT(xb_xcc_id())], 1u);
_Z14fwd_megakernel6Params:
	s_load_dwordx16 s[56:71], s[0:1], 0xc0
	s_load_dwordx2 s[88:89], s[0:1], 0x0
	s_load_dwordx2 s[90:91], s[0:1], 0x40
	s_load_dwordx2 s[92:93], s[0:1], 0x80
	s_add_u32 s4, s0, 0x100
	s_addc_u32 s5, s1, 0
	v_and_b32_e32 v250, 0x3ff, v0
	s_getpc_b64 vcc
	v_lshlrev_b32_e32 v253, 6, v250
	v_mov_b32_e32 v248, vcc_lo
	v_mov_b32_e32 v249, vcc_hi
	v_add_co_u32_e32 v248, vcc, v248, v253
	s_nop 1
	v_addc_co_u32_e32 v249, vcc, 0, v249, vcc
	global_load_dword v251, v[248:249], off
	v_add_co_u32_e32 v248, vcc, 0x8000, v248
	s_nop 1
	v_addc_co_u32_e32 v249, vcc, 0, v249, vcc
	global_load_dword v252, v[248:249], off
	v_writelane_b32 v254, s4, 0
	v_cmp_gt_u32_e32 vcc, 4, v250
	s_nop 0
	v_writelane_b32 v254, s5, 1
	s_and_saveexec_b64 s[4:5], vcc
	v_lshlrev_b32_e32 v1, 2, v250
	v_mov_b32_e32 v2, 0
	ds_write_b32 v1, v2
	s_or_b64 exec, exec, s[4:5]
	s_load_dword s33, s[0:1], 0x100
	s_waitcnt lgkmcnt(0)
	s_add_u32 s4, s70, 0x34e2100
	s_addc_u32 s5, s71, 0
	v_writelane_b32 v254, s4, 2
	v_cmp_eq_u32_e32 vcc, 0, v250
	s_nop 0
	v_writelane_b32 v254, s5, 3
	s_barrier
	s_and_saveexec_b64 s[4:5], vcc
	s_cbranch_execz .LBB0_5
	s_mov_b64 s[6:7], exec
	v_mbcnt_lo_u32_b32 v1, s6, 0
	v_mbcnt_hi_u32_b32 v1, s7, v1
	v_cmp_eq_u32_e32 vcc, 0, v1
	s_getreg_b32 s3, hwreg(HW_REG_XCC_ID, 0, 4)
	s_and_b64 s[8:9], exec, vcc
	s_mov_b64 exec, s[8:9]
	s_cbranch_execz .LBB0_5
	s_lshl_b32 s3, s3, 8
	s_bcnt1_i32_b64 s6, s[6:7]
	s_and_b32 s3, s3, 0xf00
	v_mov_b32_e32 v2, s6
	v_readlane_b32 s6, v254, 2
	v_mov_b32_e32 v1, s3
	v_readlane_b32 s7, v254, 3
	s_nop 4
	global_atomic_add v1, v2, s[6:7] offset:1024
